# attention K/V LDS-DMA issued in saddr form (SGPR tile base + loop-invariant 32-bit lane offsets) instead of per-piece 64-bit VGPR address rebuilds; on top of v020
# speedup vs baseline: 1.0095x; 1.0027x over previous
.LBB0_132:
	s_and_b32 s5, s64, 7
	s_lshl_b32 s0, s5, 8
	s_or_b32 s22, s14, s0
	s_mov_b32 s23, s15
	s_lshl_b64 s[0:1], s[22:23], 10
	s_add_u32 s0, s55, s0
	s_addc_u32 s1, s56, s1
	s_lshl_b32 s4, s64, 4
	s_and_b32 s65, s4, 0x180
	s_lshl_b32 s4, s65, 1
	s_add_u32 s30, s0, s4
	s_addc_u32 s31, s1, 0
	s_lshl_b64 s[0:1], s[2:3], 21
	s_add_u32 s3, s57, s0
	s_addc_u32 s6, s58, s1
	s_add_u32 s24, s3, s4
	s_addc_u32 s25, s6, 0
	v_mov_b32_e32 v121, v218
	s_add_u32 s0, s90, s0
	v_mov_b32_e32 v4, v218
	s_addc_u32 s1, s91, s1
	s_add_u32 s3, s0, s4
	v_ashrrev_i32_e32 v0, 6, v4
	v_and_b32_e32 v6, 31, v4
	v_readfirstlane_b32 s0, v0
	v_lshl_or_b32 v0, v0, 5, v6
	v_ashrrev_i32_e32 v1, 31, v0
	v_lshlrev_b64 v[0:1], 10, v[0:1]
	v_lshrrev_b32_e32 v7, 1, v4
	v_and_b32_e32 v5, 63, v4
	v_lshl_add_u64 v[0:1], s[30:31], 0, v[0:1]
	v_and_b32_e32 v184, 16, v7
	s_addc_u32 s66, s1, 0
	v_lshl_add_u64 v[0:1], v[0:1], 0, v[184:185]
	s_lshl_b32 s1, s0, 10
	v_lshlrev_b32_e32 v8, 4, v5
	global_load_dwordx4 v[96:99], v[0:1], off
	global_load_dwordx4 v[100:103], v[0:1], off offset:32
	global_load_dwordx4 v[104:107], v[0:1], off offset:64
	global_load_dwordx4 v[108:111], v[0:1], off offset:96
	v_or_b32_e32 v0, s1, v8
	v_ashrrev_i32_e32 v1, 31, v0
	v_lshrrev_b32_e32 v1, 25, v1
	v_add_u32_e32 v1, v0, v1
	v_lshlrev_b32_e32 v9, 3, v5
	s_lshl_b32 s0, s0, 6
	v_ashrrev_i32_e32 v2, 7, v1
	v_and_b32_e32 v1, 0xffffff80, v1
	v_and_b32_e32 v3, 32, v4
	s_and_b32 s0, s0, 64
	v_and_b32_e32 v10, 24, v9
	v_sub_u32_e32 v0, v0, v1
	v_or3_b32 v3, v10, v3, s0
	s_ashr_i32 s0, s1, 8
	v_ashrrev_i32_e32 v0, 4, v0
	v_lshrrev_b32_e32 v1, 1, v2
	s_and_b32 s6, s0, 0x7ffff0
	s_lshr_b32 s0, s0, 1
	v_bitop3_b32 v0, v1, v0, 7 bitop3:0x6c
	v_bfe_u32 v1, v4, 2, 2
	s_and_b32 s0, s0, 4
	v_and_or_b32 v1, v7, 8, v1
	s_or_b32 s0, s6, s0
	v_or_b32_e32 v10, s0, v1
	s_add_i32 s0, s1, 0x2000
	s_ashr_i32 s0, s0, 8
	s_and_b32 s6, s0, 0x7ffff0
	s_lshr_b32 s0, s0, 1
	s_and_b32 s0, s0, 4
	s_or_b32 s0, s6, s0
	s_add_i32 s4, 0, 0x14000
	v_or_b32_e32 v1, s0, v1
	s_lshl_b32 s0, s5, 17
	s_lshl_b32 s6, s5, 18
	v_lshl_or_b32 v114, v1, 9, v3
	v_lshlrev_b32_e32 v1, 9, v2
	s_add_u32 s68, s24, s6
	v_lshl_add_u32 v0, v0, 3, v1
	s_addc_u32 s69, s25, 0
	s_add_i32 s5, s1, 0
	v_ashrrev_i32_e32 v1, 31, v0
	s_add_i32 m0, s5, 0x8000
	v_lshl_or_b32 v112, v10, 9, v3
	v_lshlrev_b64 v[0:1], 1, v[0:1]
	s_add_u32 s34, s3, s6
	v_lshl_add_u64 v[2:3], s[68:69], 0, v[0:1]
	s_addc_u32 s35, s66, 0
	v_ashrrev_i32_e32 v113, 31, v112
	s_waitcnt lgkmcnt(0)
	s_barrier
	global_load_lds_dwordx4 v[2:3], off
	v_lshl_add_u64 v[2:3], v[112:113], 1, s[34:35]
	s_mov_b32 m0, s5
	v_ashrrev_i32_e32 v115, 31, v114
	global_load_lds_dwordx4 v[2:3], off
	v_lshl_add_u64 v[2:3], v[114:115], 1, s[34:35]
	s_add_i32 m0, s5, 0x2000
	s_cmp_lg_u32 0, -1
	global_load_lds_dwordx4 v[2:3], off
	v_and_b32_e32 v2, 0x3fffffc0, v4
	v_lshl_add_u32 v119, v2, 2, s4
	v_lshlrev_b32_e32 v2, 1, v4
	s_cselect_b32 s1, 0, 0
	v_and_b32_e32 v2, 32, v2
	v_lshlrev_b32_e32 v4, 3, v4
	s_add_i32 s6, s1, 0x8000
	s_movk_i32 s54, 0x118
	v_and_b32_e32 v3, 0xc0, v8
	s_waitcnt vmcnt(0)
	v_and_b32_e32 v4, 0x70, v4
	v_lshl_add_u32 v120, v6, 7, s6
	s_movk_i32 s6, 0x60
	v_lshl_add_u64 v[116:117], s[24:25], 0, v[0:1]
	v_mov_b32_e32 v194, v0
	v_lshlrev_b32_e32 v195, 1, v112
	v_lshlrev_b32_e32 v196, 1, v114
	v_and_or_b32 v0, v9, s54, v2
	v_mov_b32_e32 v14, v185
	v_mov_b32_e32 v15, v185
	v_bitop3_b32 v123, v7, v4, 16 bitop3:0x6c
	v_bitop3_b32 v124, v184, v4, 32 bitop3:0x36
	v_bitop3_b32 v125, v184, v4, 64 bitop3:0x36
	v_bitop3_b32 v126, v184, v4, s6 bitop3:0x36
	v_cmp_gt_u32_e64 s[6:7], 32, v5
	v_lshl_add_u32 v122, v6, 2, v119
	v_add3_u32 v127, v3, s1, v0
	s_or_b32 s67, s0, 0x8000
	v_mov_b32_e32 v0, v185
	v_mov_b32_e32 v1, v185
	v_mov_b32_e32 v2, v185
	v_mov_b32_e32 v3, v185
	v_mov_b32_e32 v4, v185
	v_mov_b32_e32 v5, v185
	v_mov_b32_e32 v6, v185
	v_mov_b32_e32 v7, v185
	v_mov_b32_e32 v8, v185
	v_mov_b32_e32 v9, v185
	v_mov_b32_e32 v10, v185
	v_mov_b32_e32 v11, v185
	v_mov_b32_e32 v12, v185
	v_mov_b32_e32 v13, v185
	v_mov_b64_e32 v[30:31], v[14:15]
	v_mov_b64_e32 v[46:47], v[14:15]
	v_mov_b64_e32 v[62:63], v[14:15]
	s_mov_b32 s53, 0
	v_mov_b32_e32 v128, 0
	v_mov_b32_e32 v160, 0x80000000
	v_mov_b32_e32 v161, 0x80000000
	v_mov_b32_e32 v162, 0x80000000
	v_mov_b32_e32 v163, 0x80000000
	v_mov_b32_e32 v164, 0x80000000
	v_mov_b32_e32 v165, 0x80000000
	v_mov_b32_e32 v166, 0x80000000
	v_mov_b32_e32 v167, 0x80000000
	v_mov_b32_e32 v168, 0x80000000
	v_mov_b32_e32 v169, 0x80000000
	v_mov_b32_e32 v170, 0x80000000
	v_mov_b32_e32 v171, 0x80000000
	v_mov_b32_e32 v172, 0x80000000
	v_mov_b32_e32 v173, 0x80000000
	v_mov_b32_e32 v174, 0x80000000
	v_mov_b32_e32 v175, 0x80000000
	s_mov_b32 s54, s67
	v_mov_b64_e32 v[28:29], v[12:13]
	v_mov_b64_e32 v[26:27], v[10:11]
	v_mov_b64_e32 v[24:25], v[8:9]
	v_mov_b64_e32 v[22:23], v[6:7]
	v_mov_b64_e32 v[20:21], v[4:5]
	v_mov_b64_e32 v[18:19], v[2:3]
	v_mov_b64_e32 v[16:17], v[0:1]
	v_mov_b64_e32 v[44:45], v[12:13]
	v_mov_b64_e32 v[42:43], v[10:11]
	v_mov_b64_e32 v[40:41], v[8:9]
	v_mov_b64_e32 v[38:39], v[6:7]
	v_mov_b64_e32 v[36:37], v[4:5]
	v_mov_b64_e32 v[34:35], v[2:3]
	v_mov_b64_e32 v[32:33], v[0:1]
	v_mov_b64_e32 v[60:61], v[12:13]
	v_mov_b64_e32 v[58:59], v[10:11]
	v_mov_b64_e32 v[56:57], v[8:9]
	v_mov_b64_e32 v[54:55], v[6:7]
	v_mov_b64_e32 v[52:53], v[4:5]
	v_mov_b64_e32 v[50:51], v[2:3]
	v_mov_b64_e32 v[48:49], v[0:1]
	v_mov_b32_e32 v129, 0
	s_waitcnt vmcnt(0) lgkmcnt(0)
	s_barrier
	s_and_b32 s80, s53, 1
	v_add_u32_e32 v118, v120, v123
	ds_read_b128 v[130:133], v118 offset:0
	ds_read_b128 v[134:137], v118 offset:0x1000
	s_cmp_eq_u32 s53, 31
	s_movk_i32 s0, 0x2000
	s_cbranch_scc1 .LBB0_134
.LBB0_133:
	s_and_b32 s0, s54, 0xf8000
	s_lshl_b32 s88, s0, 1
	s_lshl_b32 s0, s80, 13
	s_xor_b32 s1, s0, 0x2000
	s_add_i32 s1, s5, s1
	s_add_i32 m0, s1, 0x8000
	s_add_u32 s70, s3, s88
	s_addc_u32 s71, s66, 0
	s_add_u32 s100, s24, s88
	s_addc_u32 s101, s25, 0
	global_load_lds_dwordx4 v194, s[100:101]
	s_lshl_b32 s1, s80, 14
	s_xor_b32 s1, s1, 0x4000
	s_add_i32 s1, s5, s1
	s_mov_b32 m0, s1
	s_nop 0
	global_load_lds_dwordx4 v195, s[70:71]
	s_add_i32 m0, s1, 0x2000
	s_nop 0
	global_load_lds_dwordx4 v196, s[70:71]

.LBB0_148:
	v_mov_b32_e32 v66, v129
	s_nop 1
	v_permlane32_swap_b32_e32 v129, v66
	v_add_f32_e32 v64, v129, v66
	s_and_saveexec_b64 s[0:1], s[6:7]
	ds_write_b32 v122, v64
	s_or_b64 exec, exec, s[0:1]
	v_lshlrev_b32_e32 v64, 6, v121
	v_ashrrev_i32_e32 v65, 31, v64
	s_waitcnt lgkmcnt(0)
	v_add_u32_e32 v80, v119, v184
	v_lshl_add_u64 v[112:113], v[64:65], 2, s[12:13]
	ds_read_b128 v[64:67], v80
	ds_read_b128 v[68:71], v80 offset:32
	s_mov_b32 s5, 0
	v_mov_b32_e32 v130, 0
	v_mov_b32_e32 v131, 0
	s_waitcnt lgkmcnt(1)
	v_rcp_f32_e32 v72, v64
	v_rcp_f32_e32 v73, v65
	v_rcp_f32_e32 v74, v66
	v_rcp_f32_e32 v75, v67
	ds_read_b128 v[64:67], v80 offset:64
	s_waitcnt lgkmcnt(1)
	v_rcp_f32_e32 v68, v68
	v_rcp_f32_e32 v69, v69
	v_rcp_f32_e32 v70, v70
	v_rcp_f32_e32 v71, v71
	s_waitcnt lgkmcnt(0)
	v_rcp_f32_e32 v76, v64
	v_rcp_f32_e32 v77, v65
	v_rcp_f32_e32 v78, v66
	v_rcp_f32_e32 v79, v67
	ds_read_b128 v[64:67], v80 offset:96
	v_pk_mul_f32 v[48:49], v[48:49], v[72:73]
	v_pk_mul_f32 v[50:51], v[50:51], v[74:75]
	v_pk_mul_f32 v[32:33], v[32:33], v[72:73]
	v_pk_mul_f32 v[34:35], v[34:35], v[74:75]
	s_waitcnt lgkmcnt(0)
	v_rcp_f32_e32 v64, v64
	v_rcp_f32_e32 v65, v65
	v_rcp_f32_e32 v66, v66
	v_rcp_f32_e32 v67, v67
	v_pk_mul_f32 v[16:17], v[16:17], v[72:73]
	v_pk_mul_f32 v[18:19], v[18:19], v[74:75]
	v_pk_mul_f32 v[0:1], v[0:1], v[72:73]
	v_pk_mul_f32 v[2:3], v[2:3], v[74:75]
	flat_store_dwordx4 v[112:113], v[48:51]
	flat_store_dwordx4 v[112:113], v[32:35] offset:64
	flat_store_dwordx4 v[112:113], v[16:19] offset:128
	v_pk_mul_f32 v[48:49], v[52:53], v[68:69]
	v_pk_mul_f32 v[50:51], v[54:55], v[70:71]
	v_pk_mul_f32 v[32:33], v[36:37], v[68:69]
	v_pk_mul_f32 v[34:35], v[38:39], v[70:71]
	v_pk_mul_f32 v[16:17], v[20:21], v[68:69]
	v_pk_mul_f32 v[18:19], v[22:23], v[70:71]
	flat_store_dwordx4 v[112:113], v[0:3] offset:192
	flat_store_dwordx4 v[112:113], v[48:51] offset:16
	flat_store_dwordx4 v[112:113], v[32:35] offset:80
	v_pk_mul_f32 v[0:1], v[4:5], v[68:69]
	v_pk_mul_f32 v[2:3], v[6:7], v[70:71]
	v_pk_mul_f32 v[48:49], v[56:57], v[76:77]
	v_pk_mul_f32 v[50:51], v[58:59], v[78:79]
	v_pk_mul_f32 v[32:33], v[40:41], v[76:77]
	v_pk_mul_f32 v[34:35], v[42:43], v[78:79]
	flat_store_dwordx4 v[112:113], v[16:19] offset:144
	flat_store_dwordx4 v[112:113], v[0:3] offset:208
	flat_store_dwordx4 v[112:113], v[48:51] offset:32
	v_pk_mul_f32 v[16:17], v[24:25], v[76:77]
	v_pk_mul_f32 v[18:19], v[26:27], v[78:79]
	v_pk_mul_f32 v[0:1], v[8:9], v[76:77]
	v_pk_mul_f32 v[2:3], v[10:11], v[78:79]
	v_pk_mul_f32 v[48:49], v[60:61], v[64:65]
	v_pk_mul_f32 v[50:51], v[62:63], v[66:67]
	flat_store_dwordx4 v[112:113], v[32:35] offset:96
	flat_store_dwordx4 v[112:113], v[16:19] offset:160
	flat_store_dwordx4 v[112:113], v[0:3] offset:224
	v_pk_mul_f32 v[32:33], v[44:45], v[64:65]
	v_pk_mul_f32 v[34:35], v[46:47], v[66:67]
	v_pk_mul_f32 v[16:17], v[28:29], v[64:65]
	v_pk_mul_f32 v[18:19], v[30:31], v[66:67]
	v_pk_mul_f32 v[0:1], v[12:13], v[64:65]
	v_pk_mul_f32 v[2:3], v[14:15], v[66:67]
	v_mov_b32_e32 v4, v218
	flat_store_dwordx4 v[112:113], v[48:51] offset:48
	flat_store_dwordx4 v[112:113], v[32:35] offset:112
	flat_store_dwordx4 v[112:113], v[16:19] offset:176
	flat_store_dwordx4 v[112:113], v[0:3] offset:240
	v_mov_b32_e32 v14, v185
	v_and_b32_e32 v6, 31, v4
	v_and_b32_e32 v0, 0x3fffffc0, v4
	v_lshl_add_u32 v122, v0, 2, s4
	v_ashrrev_i32_e32 v0, 6, v4
	v_lshrrev_b32_e32 v7, 1, v4
	v_readfirstlane_b32 s0, v0
	v_lshl_or_b32 v0, v0, 5, v6
	v_ashrrev_i32_e32 v1, 31, v0
	v_lshlrev_b64 v[0:1], 10, v[0:1]
	v_and_b32_e32 v5, 63, v4
	v_lshl_add_u64 v[0:1], s[30:31], 0, v[0:1]
	v_and_b32_e32 v184, 16, v7
	v_lshl_add_u64 v[0:1], v[0:1], 0, v[184:185]
	s_lshl_b32 s1, s0, 10
	v_lshlrev_b32_e32 v8, 4, v5
	global_load_dwordx4 v[96:99], v[0:1], off offset:128
	global_load_dwordx4 v[100:103], v[0:1], off offset:160
	global_load_dwordx4 v[104:107], v[0:1], off offset:192
	global_load_dwordx4 v[108:111], v[0:1], off offset:224
	v_or_b32_e32 v0, s1, v8
	v_ashrrev_i32_e32 v1, 31, v0
	v_lshrrev_b32_e32 v1, 25, v1
	v_add_u32_e32 v1, v0, v1
	v_lshlrev_b32_e32 v9, 3, v5
	s_lshl_b32 s0, s0, 6
	v_ashrrev_i32_e32 v2, 7, v1
	v_and_b32_e32 v1, 0xffffff80, v1
	v_and_b32_e32 v3, 32, v4
	s_and_b32 s0, s0, 64
	v_and_b32_e32 v10, 24, v9
	v_sub_u32_e32 v0, v0, v1
	v_or3_b32 v3, v10, v3, s0
	s_ashr_i32 s0, s1, 8
	v_ashrrev_i32_e32 v0, 4, v0
	v_lshrrev_b32_e32 v1, 1, v2
	s_and_b32 s4, s0, 0x7ffff0
	s_lshr_b32 s0, s0, 1
	v_bitop3_b32 v0, v1, v0, 7 bitop3:0x6c
	v_bfe_u32 v1, v4, 2, 2
	s_and_b32 s0, s0, 4
	v_and_or_b32 v1, v7, 8, v1
	s_or_b32 s0, s4, s0
	v_or_b32_e32 v10, s0, v1
	s_add_i32 s0, s1, 0x2000
	s_ashr_i32 s0, s0, 8
	s_and_b32 s4, s0, 0x7ffff0
	s_lshr_b32 s0, s0, 1
	s_and_b32 s0, s0, 4
	s_or_b32 s0, s4, s0
	v_or_b32_e32 v1, s0, v1
	v_lshl_or_b32 v116, v1, 9, v3
	v_lshlrev_b32_e32 v1, 9, v2
	v_lshl_add_u32 v0, v0, 3, v1
	v_ashrrev_i32_e32 v1, 31, v0
	v_lshlrev_b64 v[0:1], 1, v[0:1]
	v_lshl_or_b32 v114, v10, 9, v3
	v_lshl_add_u64 v[2:3], s[68:69], 0, v[0:1]
	s_add_i32 s4, s1, 0
	v_lshl_add_u64 v[2:3], v[2:3], 0, s[78:79]
	s_add_i32 m0, s4, 0x8000
	v_ashrrev_i32_e32 v115, 31, v114
	s_waitcnt lgkmcnt(0)
	s_barrier
	global_load_lds_dwordx4 v[2:3], off
	v_lshl_add_u64 v[2:3], v[114:115], 1, s[34:35]
	s_mov_b32 m0, s4
	v_ashrrev_i32_e32 v117, 31, v116
	global_load_lds_dwordx4 v[2:3], off
	v_lshl_add_u64 v[2:3], v[116:117], 1, s[34:35]
	s_add_i32 m0, s4, 0x2000
	s_cmp_lg_u32 0, -1
	global_load_lds_dwordx4 v[2:3], off
	s_cselect_b32 s0, 0, 0
	v_lshlrev_b32_e32 v10, 1, v4
	v_lshlrev_b32_e32 v4, 3, v4
	s_add_i32 s1, s0, 0x8000
	v_and_b32_e32 v4, 0x70, v4
	v_lshl_add_u32 v124, v6, 7, s1
	s_movk_i32 s1, 0x60
	v_and_b32_e32 v3, 32, v10
	v_bitop3_b32 v128, v184, v4, s1 bitop3:0x36
	s_movk_i32 s1, 0x118
	v_and_b32_e32 v2, 0xc0, v8
	s_waitcnt vmcnt(0)
	v_lshl_add_u64 v[118:119], s[24:25], 0, v[0:1]
	v_mov_b32_e32 v194, v0
	v_lshlrev_b32_e32 v195, 1, v114
	v_lshlrev_b32_e32 v196, 1, v116
	s_add_u32 s100, s24, 0x80
	s_addc_u32 s101, s25, 0
	v_and_or_b32 v0, v9, s1, v3
	v_mov_b32_e32 v15, v185
	v_bitop3_b32 v125, v7, v4, 16 bitop3:0x6c
	v_bitop3_b32 v126, v184, v4, 32 bitop3:0x36
	v_bitop3_b32 v127, v184, v4, 64 bitop3:0x36
	v_cmp_gt_u32_e64 s[6:7], 32, v5
	v_lshl_add_u32 v123, v6, 2, v122
	v_add3_u32 v129, v2, s0, v0
	v_mov_b32_e32 v0, v185
	v_mov_b32_e32 v1, v185
	v_mov_b32_e32 v2, v185
	v_mov_b32_e32 v3, v185
	v_mov_b32_e32 v4, v185
	v_mov_b32_e32 v5, v185
	v_mov_b32_e32 v6, v185
	v_mov_b32_e32 v7, v185
	v_mov_b32_e32 v8, v185
	v_mov_b32_e32 v9, v185
	v_mov_b32_e32 v10, v185
	v_mov_b32_e32 v11, v185
	v_mov_b32_e32 v12, v185
	v_mov_b32_e32 v13, v185
	v_mov_b64_e32 v[30:31], v[14:15]
	v_mov_b64_e32 v[46:47], v[14:15]
	v_mov_b64_e32 v[62:63], v[14:15]
	v_mov_b64_e32 v[28:29], v[12:13]
	v_mov_b64_e32 v[26:27], v[10:11]
	v_mov_b64_e32 v[24:25], v[8:9]
	v_mov_b64_e32 v[22:23], v[6:7]
	v_mov_b64_e32 v[20:21], v[4:5]
	v_mov_b64_e32 v[18:19], v[2:3]
	v_mov_b64_e32 v[16:17], v[0:1]
	v_mov_b64_e32 v[44:45], v[12:13]
	v_mov_b64_e32 v[42:43], v[10:11]
	v_mov_b64_e32 v[40:41], v[8:9]
	v_mov_b64_e32 v[38:39], v[6:7]
	v_mov_b64_e32 v[36:37], v[4:5]
	v_mov_b64_e32 v[34:35], v[2:3]
	v_mov_b64_e32 v[32:33], v[0:1]
	v_mov_b64_e32 v[60:61], v[12:13]
	v_mov_b64_e32 v[58:59], v[10:11]
	v_mov_b64_e32 v[56:57], v[8:9]
	v_mov_b64_e32 v[54:55], v[6:7]
	v_mov_b64_e32 v[52:53], v[4:5]
	v_mov_b64_e32 v[50:51], v[2:3]
	v_mov_b64_e32 v[48:49], v[0:1]
	v_mov_b32_e32 v160, 0x80000000
	v_mov_b32_e32 v161, 0x80000000
	v_mov_b32_e32 v162, 0x80000000
	v_mov_b32_e32 v163, 0x80000000
	v_mov_b32_e32 v164, 0x80000000
	v_mov_b32_e32 v165, 0x80000000
	v_mov_b32_e32 v166, 0x80000000
	v_mov_b32_e32 v167, 0x80000000
	v_mov_b32_e32 v168, 0x80000000
	v_mov_b32_e32 v169, 0x80000000
	v_mov_b32_e32 v170, 0x80000000
	v_mov_b32_e32 v171, 0x80000000
	v_mov_b32_e32 v172, 0x80000000
	v_mov_b32_e32 v173, 0x80000000
	v_mov_b32_e32 v174, 0x80000000
	v_mov_b32_e32 v175, 0x80000000
	v_readlane_b32 s54, v254, 48
	s_waitcnt vmcnt(0) lgkmcnt(0)
	s_barrier
	s_and_b32 s53, s5, 1
	v_add_u32_e32 v120, v124, v125
	ds_read_b128 v[132:135], v120 offset:0
	ds_read_b128 v[136:139], v120 offset:0x1000
	s_cmp_eq_u32 s5, 31
	s_movk_i32 s0, 0x2000
	s_cbranch_scc1 .LBB0_152
.LBB0_151:
	s_and_b32 s0, s67, 0xf8000
	s_lshl_b32 s88, s0, 1
	s_lshl_b32 s0, s53, 13
	s_xor_b32 s1, s0, 0x2000
	s_add_i32 s1, s4, s1
	s_add_i32 m0, s1, 0x8000
	s_add_u32 s24, s3, s88
	s_addc_u32 s25, s66, 0
	s_add_u32 vcc_lo, s100, s88
	s_addc_u32 vcc_hi, s101, 0
	global_load_lds_dwordx4 v194, vcc
	s_lshl_b32 s1, s53, 14
	s_xor_b32 s1, s1, 0x4000
	s_add_i32 s1, s4, s1
	s_mov_b32 m0, s1
	s_nop 0
	global_load_lds_dwordx4 v195, s[24:25]
	s_add_i32 m0, s1, 0x2000
	s_nop 0
	global_load_lds_dwordx4 v196, s[24:25]

.LBB0_169:
	s_and_b32 s0, s64, 31
	s_lshl_b32 s0, s0, 6
	s_or_b32 s14, s14, s0
	s_mul_i32 s0, s15, 0x600
	s_mul_hi_u32 s1, s14, 0x600
	s_add_i32 s1, s1, s0
	s_mul_i32 s0, s14, 0x600
	s_add_u32 s0, s38, s0
	s_addc_u32 s1, s39, s1
	s_mul_hi_i32 s3, s2, 0xc0000
	s_mul_i32 s2, s2, 0xc0000
	v_mov_b32_e32 v158, v218
	s_add_u32 s4, s28, s2
	v_mov_b32_e32 v4, v218
	s_addc_u32 s5, s29, s3
	s_add_i32 s3, 0, 0x14000
	v_and_b32_e32 v0, 0x3fffffc0, v4
	v_lshl_add_u32 v159, v0, 2, s3
	v_ashrrev_i32_e32 v0, 6, v4
	v_and_b32_e32 v6, 31, v4
	v_readfirstlane_b32 s3, v0
	v_lshlrev_b32_e32 v0, 5, v0
	v_and_or_b32 v0, v0, 32, v6
	v_mul_u32_u24_e32 v0, 0x300, v0
	v_ashrrev_i32_e32 v2, 7, v4
	v_lshlrev_b32_e32 v184, 1, v0
	v_mul_lo_u32 v2, v2, s60
	v_lshl_add_u64 v[0:1], s[0:1], 0, v[184:185]
	v_ashrrev_i32_e32 v3, 31, v2
	v_lshl_add_u64 v[0:1], v[2:3], 1, v[0:1]
	v_lshrrev_b32_e32 v2, 1, v4
	v_and_b32_e32 v5, 63, v4
	v_and_b32_e32 v184, 16, v2
	v_lshl_add_u64 v[0:1], v[0:1], 0, v[184:185]
	s_lshl_b32 s6, s3, 10
	v_lshlrev_b32_e32 v3, 4, v5
	global_load_dwordx4 v[96:99], v[0:1], off
	global_load_dwordx4 v[100:103], v[0:1], off offset:32
	global_load_dwordx4 v[104:107], v[0:1], off offset:64
	global_load_dwordx4 v[108:111], v[0:1], off offset:96
	global_load_dwordx4 v[112:115], v[0:1], off offset:128
	global_load_dwordx4 v[116:119], v[0:1], off offset:160
	global_load_dwordx4 v[120:123], v[0:1], off offset:192
	global_load_dwordx4 v[124:127], v[0:1], off offset:224
	global_load_dwordx4 v[128:131], v[0:1], off offset:256
	global_load_dwordx4 v[132:135], v[0:1], off offset:288
	global_load_dwordx4 v[136:139], v[0:1], off offset:320
	global_load_dwordx4 v[140:143], v[0:1], off offset:352
	v_or_b32_e32 v0, s6, v3
	s_mov_b32 s0, 0x2aaaaaab
	v_mul_hi_i32 v1, v0, s0
	v_lshrrev_b32_e32 v7, 31, v1
	v_ashrrev_i32_e32 v1, 6, v1
	v_add_u32_e32 v1, v1, v7
	v_mul_i32_i24_e32 v7, 0x180, v1
	v_sub_u32_e32 v7, v0, v7
	v_ashrrev_i32_e32 v7, 4, v7
	v_lshrrev_b32_e32 v8, 1, v1
	v_bitop3_b32 v7, v8, v7, 7 bitop3:0x6c
	v_mul_i32_i24_e32 v1, 0xc0, v1
	v_lshl_add_u32 v146, v7, 3, v1
	v_add_u32_e32 v1, 0x2000, v0
	v_mul_hi_i32 v7, v1, s0
	v_lshrrev_b32_e32 v8, 31, v7
	v_ashrrev_i32_e32 v7, 6, v7
	v_add_u32_e32 v7, v7, v8
	v_mul_i32_i24_e32 v8, 0x180, v7
	v_sub_u32_e32 v1, v1, v8
	v_ashrrev_i32_e32 v1, 4, v1
	v_lshrrev_b32_e32 v8, 1, v7
	v_bitop3_b32 v1, v8, v1, 7 bitop3:0x6c
	v_mul_i32_i24_e32 v7, 0xc0, v7
	v_add_u32_e32 v0, 0x4000, v0
	v_lshl_add_u32 v148, v1, 3, v7
	v_mul_hi_i32 v1, v0, s0
	v_lshrrev_b32_e32 v7, 31, v1
	v_ashrrev_i32_e32 v1, 6, v1
	v_add_u32_e32 v1, v1, v7
	v_mul_i32_i24_e32 v7, 0x180, v1
	v_sub_u32_e32 v0, v0, v7
	v_ashrrev_i32_e32 v0, 4, v0
	v_lshrrev_b32_e32 v7, 1, v1
	v_bitop3_b32 v0, v7, v0, 7 bitop3:0x6c
	v_mul_i32_i24_e32 v1, 0xc0, v1
	v_lshlrev_b32_e32 v7, 3, v5
	s_lshl_b32 s0, s3, 6
	v_lshl_add_u32 v150, v0, 3, v1
	v_and_b32_e32 v1, 32, v4
	s_and_b32 s0, s0, 64
	v_and_b32_e32 v8, 24, v7
	v_or3_b32 v1, v8, v1, s0
	s_ashr_i32 s0, s6, 8
	s_and_b32 s1, s0, 0xfffff0
	s_lshr_b32 s0, s0, 1
	v_bfe_u32 v0, v4, 2, 2
	s_and_b32 s0, s0, 4
	v_and_or_b32 v0, v2, 8, v0
	s_or_b32 s0, s1, s0
	v_or_b32_e32 v8, s0, v0
	s_add_i32 s0, s6, 0x2000
	s_ashr_i32 s0, s0, 8
	s_lshl_b32 s2, s64, 2
	s_and_b32 s1, s0, 0xfffff0
	s_lshr_b32 s0, s0, 1
	s_and_b32 s2, s2, 28
	s_and_b32 s0, s0, 4
	s_or_b32 s0, s1, s0
	s_mulk_i32 s2, 0x6000
	v_or_b32_e32 v0, s0, v0
	s_add_u32 s0, s4, s2
	s_addc_u32 s1, s5, 0
	s_add_i32 s30, s6, 0
	v_ashrrev_i32_e32 v147, 31, v146
	v_mad_i32_i24 v152, v8, s60, v1
	v_mad_i32_i24 v154, v0, s60, v1
	s_add_i32 m0, s30, 0x8000
	v_lshl_add_u64 v[0:1], v[146:147], 1, s[0:1]
	v_ashrrev_i32_e32 v149, 31, v148
	s_waitcnt lgkmcnt(0)
	s_barrier
	global_load_lds_dwordx4 v[0:1], off
	v_lshl_add_u64 v[0:1], v[148:149], 1, s[0:1]
	s_add_i32 m0, s30, 0xa000
	v_ashrrev_i32_e32 v151, 31, v150
	global_load_lds_dwordx4 v[0:1], off
	v_lshl_add_u64 v[0:1], v[150:151], 1, s[0:1]
	s_add_i32 m0, s30, 0xc000
	v_ashrrev_i32_e32 v153, 31, v152
	global_load_lds_dwordx4 v[0:1], off
	v_lshl_add_u64 v[0:1], v[152:153], 1, s[0:1]
	s_mov_b32 m0, s30
	v_ashrrev_i32_e32 v155, 31, v154
	global_load_lds_dwordx4 v[0:1], off
	v_lshl_add_u64 v[0:1], v[154:155], 1, s[0:1]
	s_add_i32 m0, s30, 0x2000
	s_cmp_lg_u32 0, -1
	global_load_lds_dwordx4 v[0:1], off
	s_cselect_b32 s0, 0, 0
	s_add_i32 s1, s0, 0x8000
	v_lshlrev_b32_e32 v8, 1, v4
	v_lshlrev_b32_e32 v1, 3, v4
	v_mov_b32_e32 v4, s1
	s_movk_i32 s1, 0x180
	v_and_b32_e32 v1, 0x70, v1
	v_mad_u32_u24 v161, v6, s1, v4
	s_movk_i32 s1, 0x60
	v_and_b32_e32 v0, 32, v8
	v_bitop3_b32 v165, v184, v1, s1 bitop3:0x36
	s_movk_i32 s1, 0x118
	v_and_b32_e32 v3, 0xc0, v3
	v_and_or_b32 v0, v7, s1, v0
	s_waitcnt vmcnt(0)
	v_add3_u32 v166, v3, s0, v0
	s_and_b32 s0, s64, 7
	v_mov_b32_e32 v14, v185
	v_mov_b32_e32 v15, v185
	v_bitop3_b32 v162, v2, v1, 16 bitop3:0x6c
	v_bitop3_b32 v163, v184, v1, 32 bitop3:0x36
	v_bitop3_b32 v164, v184, v1, 64 bitop3:0x36
	v_cmp_gt_u32_e64 s[6:7], 32, v5
	v_lshl_add_u32 v160, v6, 2, v159
	s_lshl_b32 s0, s0, 8
	v_mov_b32_e32 v0, v185
	v_mov_b32_e32 v1, v185
	v_mov_b32_e32 v2, v185
	v_mov_b32_e32 v3, v185
	v_mov_b32_e32 v4, v185
	v_mov_b32_e32 v5, v185
	v_mov_b32_e32 v6, v185
	v_mov_b32_e32 v7, v185
	v_mov_b32_e32 v8, v185
	v_mov_b32_e32 v9, v185
	v_mov_b32_e32 v10, v185
	v_mov_b32_e32 v11, v185
	v_mov_b32_e32 v12, v185
	v_mov_b32_e32 v13, v185
	v_mov_b64_e32 v[30:31], v[14:15]
	v_mov_b64_e32 v[46:47], v[14:15]
	v_mov_b64_e32 v[62:63], v[14:15]
	s_mov_b32 s31, 0
	s_or_b32 s34, s0, 64
	v_lshlrev_b32_e32 v197, 1, v146
	v_lshlrev_b32_e32 v198, 1, v148
	v_lshlrev_b32_e32 v199, 1, v150
	v_lshlrev_b32_e32 v200, 1, v152
	v_lshlrev_b32_e32 v201, 1, v154
	v_mov_b32_e32 v167, 0
	v_mov_b64_e32 v[28:29], v[12:13]
	v_mov_b64_e32 v[26:27], v[10:11]
	v_mov_b64_e32 v[24:25], v[8:9]
	v_mov_b64_e32 v[22:23], v[6:7]
	v_mov_b64_e32 v[20:21], v[4:5]
	v_mov_b64_e32 v[18:19], v[2:3]
	v_mov_b64_e32 v[16:17], v[0:1]
	v_mov_b64_e32 v[44:45], v[12:13]
	v_mov_b64_e32 v[42:43], v[10:11]
	v_mov_b64_e32 v[40:41], v[8:9]
	v_mov_b64_e32 v[38:39], v[6:7]
	v_mov_b64_e32 v[36:37], v[4:5]
	v_mov_b64_e32 v[34:35], v[2:3]
	v_mov_b64_e32 v[32:33], v[0:1]
	v_mov_b64_e32 v[60:61], v[12:13]
	v_mov_b64_e32 v[58:59], v[10:11]
	v_mov_b64_e32 v[56:57], v[8:9]
	v_mov_b64_e32 v[54:55], v[6:7]
	v_mov_b64_e32 v[52:53], v[4:5]
	v_mov_b64_e32 v[50:51], v[2:3]
	v_mov_b64_e32 v[48:49], v[0:1]
	v_mov_b32_e32 v168, 0
	s_waitcnt vmcnt(0) lgkmcnt(0)
	s_barrier
	s_and_b32 s35, s31, 1
	s_cmp_eq_u32 s31, 31
	s_cbranch_scc1 .LBB0_171
.LBB0_170:
	s_and_b32 s0, s34, 0x7c0
	s_mulk_i32 s0, 0x180
	s_add_u32 s0, s4, s0
	s_addc_u32 s1, s5, 0
	s_xor_b32 s2, s35, 1
	s_mulk_i32 s2, 0x6000
	s_add_i32 s2, s30, s2
	s_add_i32 m0, s2, 0x8000
	s_nop 0
	global_load_lds_dwordx4 v197, s[0:1]
	s_add_i32 m0, s2, 0xa000
	s_nop 0
	global_load_lds_dwordx4 v198, s[0:1]
	s_add_i32 m0, s2, 0xc000
	s_lshl_b32 s2, s35, 14
	s_xor_b32 s2, s2, 0x4000
	s_add_i32 s2, s30, s2
	global_load_lds_dwordx4 v199, s[0:1]
	s_mov_b32 m0, s2
	s_nop 0
	global_load_lds_dwordx4 v200, s[0:1]
	s_add_i32 m0, s2, 0x2000
	s_nop 0
	global_load_lds_dwordx4 v201, s[0:1]

	.amdhsa_kernel _Z10fwd_kernel4Args
		.amdhsa_group_segment_fixed_size 0
		.amdhsa_private_segment_fixed_size 0
		.amdhsa_kernarg_size 432
		.amdhsa_user_sgpr_count 2
		.amdhsa_user_sgpr_dispatch_ptr 0
		.amdhsa_user_sgpr_queue_ptr 0
		.amdhsa_user_sgpr_kernarg_segment_ptr 1
		.amdhsa_user_sgpr_dispatch_id 0
		.amdhsa_user_sgpr_kernarg_preload_length 0
		.amdhsa_user_sgpr_kernarg_preload_offset 0
		.amdhsa_user_sgpr_private_segment_size 0
		.amdhsa_uses_dynamic_stack 0
		.amdhsa_enable_private_segment 0
		.amdhsa_system_sgpr_workgroup_id_x 1
		.amdhsa_system_sgpr_workgroup_id_y 0
		.amdhsa_system_sgpr_workgroup_id_z 0
		.amdhsa_system_sgpr_workgroup_info 0
		.amdhsa_system_vgpr_workitem_id 2
		.amdhsa_next_free_vgpr 256
		.amdhsa_next_free_sgpr 102
		.amdhsa_accum_offset 256
		.amdhsa_reserve_vcc 1
		.amdhsa_float_round_mode_32 0
		.amdhsa_float_round_mode_16_64 0
		.amdhsa_float_denorm_mode_32 3
		.amdhsa_float_denorm_mode_16_64 3
		.amdhsa_dx10_clamp 1
		.amdhsa_ieee_mode 1
		.amdhsa_fp16_overflow 0
		.amdhsa_tg_split 0
		.amdhsa_exception_fp_ieee_invalid_op 0
		.amdhsa_exception_fp_denorm_src 0
		.amdhsa_exception_fp_ieee_div_zero 0
		.amdhsa_exception_fp_ieee_overflow 0
		.amdhsa_exception_fp_ieee_underflow 0
		.amdhsa_exception_fp_ieee_inexact 0
		.amdhsa_exception_int_div_zero 0
	.end_amdhsa_kernel

amdhsa.kernels:
  - .agpr_count:     0
    .args:
      - .offset:         0
        .size:           176
        .value_kind:     by_value
      - .offset:         176
        .size:           4
        .value_kind:     hidden_block_count_x
      - .offset:         180
        .size:           4
        .value_kind:     hidden_block_count_y
      - .offset:         184
        .size:           4
        .value_kind:     hidden_block_count_z
      - .offset:         188
        .size:           2
        .value_kind:     hidden_group_size_x
      - .offset:         190
        .size:           2
        .value_kind:     hidden_group_size_y
      - .offset:         192
        .size:           2
        .value_kind:     hidden_group_size_z
      - .offset:         194
        .size:           2
        .value_kind:     hidden_remainder_x
      - .offset:         196
        .size:           2
        .value_kind:     hidden_remainder_y
      - .offset:         198
        .size:           2
        .value_kind:     hidden_remainder_z
      - .offset:         216
        .size:           8
        .value_kind:     hidden_global_offset_x
      - .offset:         224
        .size:           8
        .value_kind:     hidden_global_offset_y
      - .offset:         232
        .size:           8
        .value_kind:     hidden_global_offset_z
      - .offset:         240
        .size:           2
        .value_kind:     hidden_grid_dims
      - .offset:         264
        .size:           8
        .value_kind:     hidden_multigrid_sync_arg
      - .offset:         296
        .size:           4
        .value_kind:     hidden_dynamic_lds_size
    .group_segment_fixed_size: 0
    .kernarg_segment_align: 8
    .kernarg_segment_size: 432
    .language:       OpenCL C
    .language_version:
      - 2
      - 0
    .max_flat_workgroup_size: 512
    .name:           _Z10fwd_kernel4Args
    .private_segment_fixed_size: 0
    .sgpr_count:     108
    .sgpr_spill_count: 133
    .symbol:         _Z10fwd_kernel4Args.kd
    .uniform_work_group_size: 1
    .uses_dynamic_stack: false
    .vgpr_count:     256
    .vgpr_spill_count: 0
    .wavefront_size: 64
